# P2 work queue: next ticket atomic prefetched (result parked in a VGPR) instead of issue+wait per item
# baseline (speedup 1.0000x reference)
; #define LAS __attribute__((address_space(3)))
; __global__ void __launch_bounds__(512, 2) fwd_megakernel(Args a) {
;     ...
;         constexpr int N_LRUA = NSEG * 16, N_ATTP = 64 * 16, N_ATTS = 256, N_LRUS = 256, N_LRUB = NSEG * 16;
;         constexpr int Q1 = N_LRUA, Q2 = Q1 + N_ATTP, Q3 = Q2 + N_ATTS, Q4 = Q3 + N_LRUS, NITEMS = Q4 + N_LRUB;
;         LAS int* slot = (LAS int*)(lds + 140 * 1024);
;         for (;;) {
;             if (tid == 0) *slot = (int)atomicAdd((unsigned*)(ws + WS_CTL), 1u);
;             __syncthreads();
;             const int it0 = __builtin_amdgcn_readfirstlane(*slot);
.LBB0_395:
	v_writelane_b32 v254, s94, 44
	s_nop 1
	v_writelane_b32 v254, s95, 45
	s_or_b64 exec, exec, s[0:1]
	s_add_u32 s20, s88, 0x7c00
	s_addc_u32 s21, s89, 0
	s_add_u32 s46, s88, 0x171000
	s_addc_u32 s47, s89, 0
	s_add_u32 s0, s86, 0xc503000
	s_addc_u32 s1, s87, 0
	s_add_u32 s22, s88, 0x14000000
	s_addc_u32 s23, s89, 0
	s_add_u32 s26, s88, 0x18400000
	s_addc_u32 s27, s89, 0
	s_add_u32 s28, s88, 0x1a600000
	s_addc_u32 s29, s89, 0
	v_writelane_b32 v254, s0, 46
	s_add_u32 s30, s88, 0x7400000
	s_addc_u32 s31, s89, 0
	v_writelane_b32 v254, s1, 47
	s_add_u32 s34, s88, 0x5200000
	v_readlane_b32 s2, v254, 21
	s_addc_u32 s35, s89, 0
	s_lshl_b32 s0, s2, 4
	s_and_b32 s69, s0, 48
	s_lshl_b32 s0, s69, 2
	s_add_u32 s1, s78, s0
	v_writelane_b32 v254, s1, 32
	s_addc_u32 s1, s79, 0
	v_writelane_b32 v254, s1, 34
	s_add_u32 s1, s82, s0
	v_writelane_b32 v254, s1, 36
	s_addc_u32 s1, s83, 0
	v_writelane_b32 v254, s1, 38
	s_add_i32 s0, s0, 0
	v_writelane_b32 v254, s0, 40
	s_lshr_b32 s0, s48, 3
	s_and_b32 s66, s0, 0x1fffffe0
	s_or_b32 s67, s66, 16
	s_add_u32 s0, s88, 0x9600000
	s_addc_u32 s1, s89, 0
	s_add_u32 s38, s88, 0xb800000
	v_writelane_b32 v254, s0, 26
	s_addc_u32 s39, s89, 0
	s_waitcnt lgkmcnt(0)
	v_mov_b32_e32 v0, 0
	v_writelane_b32 v254, s1, 27
	s_add_u32 s0, s88, 0x200000
	v_writelane_b32 v254, s0, 28
	s_addc_u32 s0, s89, 0
	v_writelane_b32 v254, s0, 30
	s_lshl_b32 s0, s2, 5
	s_and_b32 s1, s0, 32
	v_writelane_b32 v254, s0, 25
	s_add_u32 s0, s88, 0x170000
	v_writelane_b32 v254, s0, 48
	s_addc_u32 s0, s89, 0
	s_add_u32 s40, s88, 0xda00000
	s_addc_u32 s41, s89, 0
	s_lshr_b32 s3, s48, 7
	v_writelane_b32 v254, s0, 49
	s_add_u32 s0, s88, 0x160000
	v_writelane_b32 v254, s0, 50
	s_addc_u32 s0, s89, 0
	v_writelane_b32 v254, s0, 51
	s_add_u32 s0, s88, 0x400000
	v_writelane_b32 v254, s0, 52
	s_addc_u32 s0, s89, 0
	v_writelane_b32 v254, s0, 53
	s_cmpk_lt_u32 s48, 0x100
	s_mul_i32 s0, s3, 0x2400
	s_cselect_b64 s[42:43], -1, 0
	s_add_i32 s4, s0, 0
	s_lshl_b32 s0, s3, 10
	v_writelane_b32 v254, s4, 54
	s_add_i32 s4, s4, s0
	s_mul_i32 s0, s3, 0xffffd900
	v_writelane_b32 v254, s4, 55
	s_add_i32 s0, s4, s0
	s_or_b32 s24, s1, 0x7c1
	v_writelane_b32 v254, s0, 56
	s_cmpk_lt_u32 s48, 0x80
	v_writelane_b32 v254, s1, 57
	s_cselect_b64 s[0:1], -1, 0
	v_writelane_b32 v254, s0, 58
	v_mbcnt_lo_u32_b32 v1, -1, 0
	s_movk_i32 s94, 0x1000
	v_writelane_b32 v254, s1, 59
	s_mul_i32 s0, s2, 0x2200
	s_add_i32 s4, s0, 0
	s_cmp_eq_u32 s3, 1
	s_cselect_b64 s[0:1], -1, 0
	s_add_u32 s60, s88, 0x158000
	s_addc_u32 s61, s89, 0
	v_writelane_b32 v254, s0, 60
	s_cmpk_gt_u32 s48, 0x1ff
	s_mulk_i32 s2, 0xde04
	v_writelane_b32 v254, s1, 61
	s_cselect_b64 s[0:1], -1, 0
	s_cmpk_lt_u32 s48, 0x200
	s_cselect_b64 s[6:7], -1, 0
	v_writelane_b32 v254, s6, 23
	s_lshl_b32 s51, s3, 6
	s_movk_i32 s95, 0x2000
	v_writelane_b32 v254, s7, 24
	v_writelane_b32 v254, s3, 62
	s_add_u32 s3, s88, 0x160008
	v_writelane_b32 v254, s3, 63
	s_addc_u32 s3, s89, 0
	v_writelane_b32 v255, s3, 0
	s_sub_i32 s3, 0, s66
	s_add_i32 s33, 0, 0x23000
	v_writelane_b32 v255, s4, 1
	s_add_i32 s2, s4, s2
	v_writelane_b32 v254, s3, 42
	v_mov_b32_e32 v127, 1.0
	v_mov_b32_e32 v130, 0x3ecc95a3
	v_mov_b32_e32 v131, 0x260
	v_writelane_b32 v255, s2, 2
	s_xor_b64 s[70:71], s[0:1], -1
	v_mov_b32_e32 v133, 1
	v_mov_b32_e32 v135, s33
	v_mov_b32_e32 v136, 0x7f800000
	v_mov_b32_e32 v137, 0xff800000
	v_mbcnt_hi_u32_b32 v138, -1, v1
	s_movk_i32 s45, 0x110
	s_movk_i32 s25, 0x90
	s_mov_b32 s36, 0xf800000
	s_mov_b32 s37, 0xff800000
	s_mov_b32 s73, 0
	s_mov_b64 s[78:79], 0x1000
	v_mov_b32_e32 v252, 0
	v_mov_b32_e32 v253, 1
	s_mov_b64 s[0:1], exec
	v_readlane_b32 s2, v254, 1
	v_readlane_b32 s3, v254, 2
	s_nop 3
	s_and_b64 s[2:3], s[0:1], s[2:3]
	s_mov_b64 exec, s[2:3]
	s_cbranch_execz .Ldq_skip
	global_atomic_add v253, v252, v253, s[88:89] sc0
.Ldq_skip:
	s_mov_b64 exec, s[0:1]
	s_barrier
	s_branch .LBB0_399

; __global__ void __launch_bounds__(512, 2) fwd_megakernel(Args a) {
;     ...
;         for (;;) {
;             if (tid == 0) *slot = (int)atomicAdd((unsigned*)(ws + WS_CTL), 1u);
;             __syncthreads();
;             const int it0 = __builtin_amdgcn_readfirstlane(*slot);
;             __syncthreads();
;             if (it0 >= NITEMS) break;
;             int it = it0;
;             if (it0 >= Q1 && it0 < Q3) { const int idx = it0 - Q1, grp = (int)(((unsigned)idx * 52429u) >> 18), r = idx - grp * 5;
;                 it = r < 4 ? Q1 + grp * 4 + r : Q2 + grp; }
.LBB0_399:
	s_mov_b64 s[0:1], exec
	v_readlane_b32 s2, v254, 1
	v_readlane_b32 s3, v254, 2
	s_and_b64 s[2:3], s[0:1], s[2:3]
	s_mov_b64 exec, s[2:3]
	s_cbranch_execz .LBB0_403
	s_mov_b64 s[4:5], exec
	v_mbcnt_lo_u32_b32 v1, s4, 0
	v_mbcnt_hi_u32_b32 v1, s5, v1
	v_cmp_eq_u32_e32 vcc, 0, v1
	s_and_saveexec_b64 s[2:3], vcc
	s_cbranch_execz .LBB0_402
	s_bcnt1_i32_b64 s4, s[4:5]
	s_waitcnt vmcnt(0)
	v_mov_b32_e32 v2, v253
	v_mov_b32_e32 v253, s4
	global_atomic_add v253, v252, v253, s[88:89] sc0
.LBB0_402:
	s_or_b64 exec, exec, s[2:3]
	v_readfirstlane_b32 s2, v2
	v_mov_b32_e32 v2, s33
	s_nop 0
	v_add_u32_e32 v1, s2, v1
	ds_write_b32 v2, v1
